# LN phase: ln_g/ln_b loads hoisted out of row loop; plus pipelined intra tr-reads and relaxed loop-head vmcnt in scan loops
# speedup vs baseline: 1.0348x; 1.0348x over previous
; template <bool ISM>
; __device__ void scan_item(const Params& p, int l, int item, unsigned char* lds) {
;     ...
;     const unsigned trK = ldsb + LS_K + (unsigned)(((fq * 8 + trq) * LDK + 16 * wid + 4 * trp) * 2);
;     const unsigned trVw = ldsb + LS_VW + (unsigned)(((fq * 8 + trq) * LDV + 4 * trp) * 2);
;     const unsigned trV = ldsb + LS_V + (unsigned)(((fq * 4 + trq) * LDV + 4 * trp) * 2);
;     const float Dh = ISM ? 0.f : p.d_skip[l * 32 + h];
;     const u16* __restrict__ gQKX = p.QKX; const u16* __restrict__ gP = p.P; const float* __restrict__ gG2 = p.G2;
;     const int gcol = ISM ? (dir * 8 + h) * 3 : 48 + (dir * 32 + h) * 2;
;     __syncthreads();
;     for (int i = tid; i < 128 * 24; i += 512) { const int r = i / 24, cc = 64 + i % 24; Vs[r * LDV + cc] = (ISM && cc == 64) ? (u16)0x3F80 : (u16)0; Vw[r * LDV + cc] = 0; }
;     for (int i = tid; i < 80 * LDK; i += 512) CT[i] = 0;
;     f32x4 st[NT];
; #pragma unroll
;     for (int m = 0; m < NT; ++m) st[m] = (f32x4){0.f, 0.f, 0.f, 0.f};
;     float m_prev = 0.f;
;     unsigned qo, ko[4], vo[2], go, ge, oo[4];
;     bf16x8 qf[4]; u32x4 kr[4]; u32x4 vr[2]; f32x3 gv = {0.f, 0.f, 0.f}; float e0 = 0.f, e1 = 0.f;
;     ...
;     SCAN_PTRS(0); SCAN_LOAD();
;     const int dr_ctx = dir ? -128 : 128, dr_lat = ISM ? dr_ctx : (dir ? -1 : 1);
;     __syncthreads();
.LBB0_29:
	s_or_b64 exec, exec, s[4:5]
	v_or_b32_e32 v37, s11, v21
	s_and_b64 s[4:5], s[6:7], exec
	s_movk_i32 s3, 0x3400
	v_sub_u32_e32 v39, 0xff, v37
	s_cselect_b32 s3, s3, 0x800
	s_add_i32 s4, s13, s12
	v_cndmask_b32_e64 v39, v39, v37, s[6:7]
	s_mulk_i32 s4, 0xb0
	v_or_b32_e32 v38, s14, v19
	v_add_u32_e32 v39, s12, v39
	s_add_i32 s13, s4, s16
	v_mad_u64_u32 v[198:199], s[4:5], v39, s3, v[38:39]
	v_or_b32_e32 v39, 1, v37
	v_sub_u32_e32 v40, 0xff, v39
	v_cndmask_b32_e64 v40, v40, v39, s[6:7]
	v_add_u32_e32 v40, s12, v40
	v_mad_u64_u32 v[196:197], s[4:5], v40, s3, v[38:39]
	v_or_b32_e32 v40, 2, v37
	v_sub_u32_e32 v41, 0xff, v40
	v_cndmask_b32_e64 v41, v41, v40, s[6:7]
	v_add_u32_e32 v41, s12, v41
	v_mad_u64_u32 v[194:195], s[4:5], v41, s3, v[38:39]
	v_or_b32_e32 v41, 3, v37
	v_sub_u32_e32 v42, 0xff, v41
	v_cndmask_b32_e64 v42, v42, v41, s[6:7]
	s_lshl_b32 s15, s15, 7
	v_add_u32_e32 v42, s12, v42
	s_add_i32 s58, s13, 0x5750
	v_mad_u64_u32 v[192:193], s[4:5], v42, s3, v[38:39]
	s_and_b64 s[4:5], s[6:7], exec
	v_readlane_b32 s4, v254, 31
	v_lshlrev_b32_e32 v24, 2, v24
	s_cselect_b32 s4, 0x8a04000, s4
	v_readlane_b32 s12, v254, 25
	v_and_b32_e32 v42, 12, v24
	s_add_u32 s30, s12, s4
	v_add_u32_e32 v31, v31, v42
	v_readlane_b32 s4, v254, 4
	v_readlane_b32 s13, v254, 26
	s_mov_b32 s59, s36
	v_lshl_add_u32 v153, v31, 1, s4
	v_add_u32_e32 v31, v32, v42
	v_readlane_b32 s4, v254, 5
	s_addc_u32 s31, s13, 0
	v_readlane_b32 s12, v254, 6
	v_lshl_add_u32 v159, v31, 1, s4
	s_lshl_b64 s[4:5], s[58:59], 2
	s_add_u32 s4, s74, s4
	s_addc_u32 s5, s75, s5
	global_load_dword v225, v149, s[4:5] offset:4
	v_readlane_b32 s13, v254, 7
	v_readlane_b32 s20, v254, 8
	v_readlane_b32 s21, v254, 9
	v_or_b32_e32 v43, s11, v42
	v_add_u32_e32 v161, s12, v24
	v_add_u32_e32 v163, s13, v24
	v_add_u32_e32 v165, s20, v24
	v_add_u32_e32 v167, s21, v24
	v_sub_u32_e32 v24, 0x1fff, v30
	v_add_u32_e32 v33, v43, v33
	v_cndmask_b32_e64 v24, v24, v30, s[6:7]
	v_lshl_add_u32 v151, v33, 1, 0
	s_and_b64 s[4:5], s[6:7], exec
	v_lshlrev_b32_e32 v33, 6, v24
	s_cselect_b32 s59, s76, 0xffffff80
	s_cselect_b32 s63, 1, -1
	s_bitset1_b32 s15, 9
	v_and_b32_e32 v33, 0x1fc0, v33
	v_lshrrev_b32_e32 v24, 7, v24
	v_add3_u32 v24, v24, s15, v33
	v_mad_u64_u32 v[170:171], s[4:5], v24, s92, v[20:21]
	s_and_b64 s[4:5], s[6:7], exec
	s_movk_i32 s4, 0x7f
	s_cselect_b32 s4, s4, 0x1f80
	s_lshl_b32 s5, s4, 6
	s_lshr_b32 s4, s4, 7
	s_and_b32 s5, s5, 0x1fc0
	s_or_b32 s4, s4, s15
	s_add_i32 s4, s4, s5
	s_mul_i32 s66, s4, 0xb0
	s_add_i32 s66, s66, s16
	s_cmp_gt_i32 s18, -1
	s_cselect_b64 s[34:35], -1, 0
	s_cmp_gt_i32 s18, 1
	s_cselect_b64 s[42:43], -1, 0
	s_cmp_lt_i32 s18, 2
	v_xor_b32_e32 v20, 0x1fff, v36
	s_cselect_b64 s[44:45], -1, 0
	s_cmp_gt_i32 s18, 3
	v_cndmask_b32_e64 v20, v20, v36, s[6:7]
	s_cselect_b64 s[48:49], -1, 0
	s_cmp_lt_i32 s18, 4
	v_lshlrev_b32_e32 v24, 6, v20
	v_lshrrev_b32_e32 v20, 7, v20
	s_cselect_b64 s[52:53], -1, 0
	s_cmp_gt_i32 s18, 5
	v_and_b32_e32 v24, 0x1fc0, v24
	v_or_b32_e32 v20, s15, v20
	s_cselect_b64 s[54:55], -1, 0
	s_cmp_lt_i32 s18, 6
	v_add_u32_e32 v20, v20, v24
	s_movk_i32 s19, 0xb0
	v_readlane_b32 s5, v254, 3
	s_cselect_b64 s[56:57], -1, 0
	s_lshl_b32 s4, s11, 1
	v_mul_lo_u32 v20, v20, s19
	v_lshlrev_b32_e32 v24, 1, v19
	s_add_i32 s4, s5, s4
	v_add_u32_e32 v169, s16, v20
	v_lshlrev_b32_e32 v20, 1, v25
	v_add_u32_e32 v25, 0, v24
	v_add_u32_e32 v24, s4, v24
	s_movk_i32 s4, 0x110
	v_sub_u32_e32 v43, 0x1fff, v29
	v_lshl_add_u32 v200, v30, 2, s13
	v_mul_lo_u32 v30, v29, s4
	v_cndmask_b32_e64 v29, v43, v29, s[6:7]
	v_lshlrev_b32_e32 v43, 6, v29
	v_and_b32_e32 v43, 0x1fc0, v43
	v_lshrrev_b32_e32 v29, 7, v29
	v_add3_u32 v29, v29, s15, v43
	v_lshl_add_u32 v31, v34, 1, 0
	v_lshl_add_u32 v32, v35, 1, 0
	v_add_u32_e32 v171, 0, v20
	v_add_u32_e32 v20, s5, v20
	v_mul_lo_u32 v33, v28, s4
	v_mul_lo_u32 v34, v27, s4
	v_mul_lo_u32 v35, v26, s4
	v_mad_u64_u32 v[172:173], s[4:5], v29, s92, v[16:17]
	v_sub_u32_e32 v29, 0x1fff, v28
	v_cndmask_b32_e64 v28, v29, v28, s[6:7]
	v_lshlrev_b32_e32 v29, 6, v28
	v_and_b32_e32 v29, 0x1fc0, v29
	v_lshrrev_b32_e32 v28, 7, v28
; template <bool ISM>
; __device__ void scan_item(const Params& p, int l, int item, unsigned char* lds) {
;     ...
;     SCAN_PTRS(0); SCAN_LOAD();
;     const int dr_ctx = dir ? -128 : 128, dr_lat = ISM ? dr_ctx : (dir ? -1 : 1);
;     __syncthreads();
	v_add3_u32 v28, v28, s15, v29
	v_mad_u64_u32 v[174:175], s[4:5], v28, s92, v[16:17]
	v_sub_u32_e32 v28, 0x1fff, v27
	v_cndmask_b32_e64 v27, v28, v27, s[6:7]
	v_lshlrev_b32_e32 v28, 6, v27
	v_and_b32_e32 v28, 0x1fc0, v28
	v_lshrrev_b32_e32 v27, 7, v27
	v_add3_u32 v27, v27, s15, v28
	v_mad_u64_u32 v[176:177], s[4:5], v27, s92, v[16:17]
	v_sub_u32_e32 v27, 0x1fff, v26
	v_cndmask_b32_e64 v26, v27, v26, s[6:7]
	v_lshlrev_b32_e32 v27, 6, v26
	v_and_b32_e32 v27, 0x1fc0, v27
	v_lshrrev_b32_e32 v26, 7, v26
	v_add3_u32 v26, v26, s15, v27
	v_mad_u64_u32 v[178:179], s[4:5], v26, s92, v[16:17]
	v_sub_u32_e32 v16, 0x1fff, v22
	v_cndmask_b32_e64 v16, v16, v22, s[6:7]
	v_lshlrev_b32_e32 v26, 6, v16
	v_and_b32_e32 v26, 0x1fc0, v26
	v_lshrrev_b32_e32 v16, 7, v16
	v_add3_u32 v16, v16, s15, v26
	v_mad_u64_u32 v[180:181], s[4:5], v16, s92, v[18:19]
	v_sub_u32_e32 v16, 0x1fff, v23
	v_cndmask_b32_e64 v16, v16, v23, s[6:7]
	v_lshlrev_b32_e32 v26, 6, v16
	v_and_b32_e32 v26, 0x1fc0, v26
	v_lshrrev_b32_e32 v16, 7, v16
	v_add3_u32 v16, v16, s15, v26
	v_mad_u64_u32 v[182:183], s[4:5], v16, s92, v[18:19]
	v_sub_u32_e32 v16, 0x1fff, v37
	v_cndmask_b32_e64 v16, v16, v37, s[6:7]
	v_lshlrev_b32_e32 v18, 6, v16
	v_and_b32_e32 v18, 0x1fc0, v18
	v_lshrrev_b32_e32 v16, 7, v16
	v_add3_u32 v16, v16, s15, v18
	v_mad_u64_u32 v[184:185], s[4:5], v16, s3, v[38:39]
	v_sub_u32_e32 v16, 0x1fff, v39
	v_cndmask_b32_e64 v16, v16, v39, s[6:7]
	v_lshlrev_b32_e32 v18, 6, v16
	v_and_b32_e32 v18, 0x1fc0, v18
	v_lshrrev_b32_e32 v16, 7, v16
	v_add3_u32 v16, v16, s15, v18
	v_mad_u64_u32 v[186:187], s[4:5], v16, s3, v[38:39]
	v_sub_u32_e32 v16, 0x1fff, v40
	s_cmp_lt_i32 s18, 1
	v_cndmask_b32_e64 v16, v16, v40, s[6:7]
	s_cselect_b64 s[76:77], -1, 0
	s_cmp_lt_i32 s18, 3
	v_lshlrev_b32_e32 v18, 6, v16
	s_cselect_b64 s[78:79], -1, 0
	s_cmp_eq_u32 s18, 2
	v_and_b32_e32 v18, 0x1fc0, v18
	v_lshrrev_b32_e32 v16, 7, v16
	s_cselect_b64 s[80:81], -1, 0
	s_cmp_lt_i32 s18, 5
	v_add3_u32 v16, v16, s15, v18
	s_cselect_b64 s[82:83], -1, 0
	s_cmp_eq_u32 s18, 4
	v_mad_u64_u32 v[188:189], s[4:5], v16, s3, v[38:39]
	v_sub_u32_e32 v16, 0x1fff, v41
	s_cselect_b64 s[84:85], -1, 0
	s_cmp_lt_i32 s18, 7
	v_cndmask_b32_e64 v16, v16, v41, s[6:7]
	s_cselect_b64 s[86:87], -1, 0
	s_cmp_eq_u32 s18, 6
	v_lshlrev_b32_e32 v18, 6, v16
	s_cselect_b64 s[88:89], -1, 0
	s_cmp_lt_u32 s10, 64
	v_and_b32_e32 v18, 0x1fc0, v18
	v_lshrrev_b32_e32 v16, 7, v16
	s_cselect_b64 s[90:91], -1, 0
	s_cmp_eq_u32 s18, 1
	v_add3_u32 v16, v16, s15, v18
	s_cselect_b64 s[92:93], -1, 0
	s_cmp_eq_u32 s18, 3
	v_mad_u64_u32 v[190:191], s[4:5], v16, s3, v[38:39]
	v_or_b32_e32 v16, 2, v21
	s_cselect_b64 s[94:95], -1, 0
	s_cmp_eq_u32 s18, 5
	v_cmp_gt_u32_e64 s[14:15], v16, v19
	v_or_b32_e32 v16, 3, v21
	s_cselect_b64 s[96:97], -1, 0
	s_cmp_lt_i32 s18, 8
	v_mul_lo_u32 v36, v22, s19
	v_mul_lo_u32 v42, v23, s19
	v_mul_u32_u24_e32 v173, 0x110, v19
	v_cmp_gt_u32_e64 s[16:17], v16, v19
	s_cselect_b64 s[98:99], -1, 0
	s_cmp_eq_u32 s18, 7
	v_mul_lo_u32 v18, v37, s19
	v_mul_u32_u24_e32 v17, 0x440, v17
	v_mov_b32_e32 v16, 0
	v_lshl_add_u32 v201, v21, 2, s12
	v_cmp_gt_u32_e64 s[10:11], v21, v19
	v_cmp_lt_u32_e64 s[12:13], v21, v19
	s_cselect_b64 s[4:5], -1, 0
	v_lshl_add_u32 v175, v22, 2, s21
	v_lshl_add_u32 v177, v23, 2, s21
	v_lshl_add_u32 v179, v37, 2, s20
	v_lshl_add_u32 v181, v39, 2, s20
	v_lshl_add_u32 v183, v40, 2, s20
	v_lshl_add_u32 v185, v41, 2, s20
	s_mov_b32 s67, 0
	v_add_u32_e32 v187, v31, v30
	v_add_u32_e32 v189, v31, v33
	v_add_u32_e32 v191, v31, v34
	v_add_u32_e32 v202, v31, v35
	v_add_u32_e32 v203, v20, v173
	v_add_u32_e32 v204, v24, v17
	v_add_u32_e32 v205, v32, v36
	v_add_u32_e32 v223, v32, v42
	v_add_u32_e32 v224, v25, v18
	v_mov_b32_e32 v17, v16
	v_mov_b32_e32 v18, v16
	v_mov_b32_e32 v19, v16
	v_mov_b32_e32 v20, v16
	v_mov_b32_e32 v21, v16
	v_mov_b32_e32 v22, v16
	v_mov_b32_e32 v23, v16
	v_mov_b32_e32 v24, v16
	v_mov_b32_e32 v25, v16
	v_mov_b32_e32 v26, v16
	v_mov_b32_e32 v27, v16
	v_mov_b32_e32 v28, v16
	v_mov_b32_e32 v29, v16
	v_mov_b32_e32 v30, v16
	v_mov_b32_e32 v31, v16
	s_waitcnt lgkmcnt(0)
	s_barrier
	s_waitcnt vmcnt(0)
	s_branch .LBB0_31

; template <bool ISM>
; __device__ void scan_item(const Params& p, int l, int item, unsigned char* lds) {
;     ...
;     for (int c = 0; c < 66; ++c) {
; #pragma unroll
;         for (int rep = 0; rep < 4; ++rep) { const int idx = rep * 512 + tid; *(u32x4*)(Ks + (idx >> 4) * LDK + (idx & 15) * 8) = kr[rep]; }
; #pragma unroll
;         for (int rep = 0; rep < 2; ++rep) { const int idx = rep * 512 + tid; *(u32x4*)(Vs + (idx >> 3) * LDV + (idx & 7) * 8) = vr[rep]; }
;         float decay;
;         if (ISM) {
;             const float Ml = fmaxf(m_prev, e1);
;             if (tid < 128) { const float M = fmaxf(m_prev, gv[2]);
;                 f_c[tid] = gv[1] * L2E; f_r[tid] = M * L2E; f_wi[tid] = __expf(m_prev - M); f_ws[tid] = __expf(gv[1] - Ml); f_em[tid] = __expf(-(gv[0] + M)); }
;             decay = __expf(m_prev - Ml); m_prev = e0 + Ml;
;         } else {
;             if (tid < 128) { f_c[tid] = (__logf(gv[0]) - gv[1]) * L2E; f_r[tid] = -gv[1] * L2E; f_wi[tid] = __expf(gv[1]); f_ws[tid] = __expf(e0 - gv[1]) * gv[0]; }
;             decay = __expf(e0);
;         }
.LBB0_31:
	ds_write_b128 v187, v[0:3]
	ds_write_b128 v189, v[4:7]
	ds_write_b128 v191, v[8:11]
	ds_write_b128 v202, v[12:15]
	ds_write_b128 v205, v[76:79] offset:34816
	ds_write_b128 v223, v[72:75] offset:34816
	s_and_saveexec_b64 s[18:19], s[8:9]
	s_cbranch_execz .LBB0_33
	v_cmp_gt_f32_e32 vcc, s41, v144
	s_nop 1
	v_cndmask_b32_e64 v32, 0, 32, vcc
	v_ldexp_f32 v32, v144, v32
	v_log_f32_e32 v32, v32
	v_cndmask_b32_e32 v33, 0, v218, vcc
	v_mul_f32_e32 v34, 0x3f317217, v32
	v_fma_f32 v34, v32, s61, -v34
	v_fmac_f32_e32 v34, 0x3377d1cf, v32
	v_fmac_f32_e32 v34, 0x3f317217, v32
	v_cmp_lt_f32_e64 vcc, |v32|, s64
	s_nop 1
	v_cndmask_b32_e32 v32, v32, v34, vcc
	v_sub_f32_e32 v32, v32, v33
	v_sub_f32_e32 v32, v32, v145
	v_sub_f32_e32 v33, v225, v145
	v_mul_f32_e32 v32, 0x3fb8aa3b, v32
	v_mul_f32_e32 v33, 0x3fb8aa3b, v33
	ds_write_b32 v161, v32
	v_mul_f32_e32 v32, 0x3fb8aa3b, v145
	v_exp_f32_e32 v33, v33
	v_exp_f32_e32 v32, v32
	v_mul_f32_e32 v34, 0xbfb8aa3b, v145
	ds_write_b32 v163, v34
	ds_write_b32 v165, v32
	v_mul_f32_e32 v32, v144, v33
	ds_write_b32 v167, v32

; __device__ __forceinline__ float bflo(unsigned w) { return __uint_as_float(w << 16); }
; __device__ __forceinline__ float bfhi(unsigned w) { return __uint_as_float(w & 0xFFFF0000u); }
; __device__ __forceinline__ unsigned pk2(float lo, float hi) { const f32x2_t v = {lo, hi}; return __builtin_bit_cast(unsigned, __builtin_convertvector(v, bf16x2_t)); }
; template <bool ISM>
; __device__ void scan_item(const Params& p, int l, int item, unsigned char* lds) {
;     ...
; #pragma unroll
;           for (int rep = 0; rep < 2; ++rep) { const int idx = rep * 512 + tid; const int i = idx >> 3; const float wv = f_ws[i]; const u32x4 vc = rep ? vc1 : vc0; u32x4 o;
; #pragma unroll
;               for (int e = 0; e < 4; ++e) o[e] = pk2(bflo(vc[e]) * wv, bfhi(vc[e]) * wv);
;               *(u32x4*)(Vw + i * LDV + (idx & 7) * 8) = o; }
;           if (ISM && tid < 128) Vw[tid * LDV + 64] = f2bf(f_ws[tid]); }
;         { f32x4 ia[NT], ib[4];
; #pragma unroll
;           for (int n = 0; n < NT; ++n) ia[n] = (f32x4){0.f, 0.f, 0.f, 0.f};
; #pragma unroll
;           for (int n = 0; n < 4; ++n) ib[n] = (f32x4){0.f, 0.f, 0.f, 0.f};
; #pragma unroll
;           for (int ksd = 0; ksd < 4; ++ksd) { bf16x8 bfr[NT];
; #pragma unroll
;               for (int n = 0; n < NT; ++n) bfr[n] = *(const bf16x8*)(CT + (n * 16 + fr) * LDK + ksd * 32 + fq * 8);
; #pragma unroll
;               for (int n = 0; n < NT; ++n) ia[n] = __builtin_amdgcn_mfma_f32_16x16x32_bf16(qc[ksd], bfr[n], ia[n], 0, 0, 0); }
;     ...
;           SCAN_IB(0) SCAN_IB(1) SCAN_IB(2) SCAN_IB(3)
.LBB0_111:
	ds_read_b32 v80, v175
	v_lshlrev_b32_e32 v82, 16, v76
	v_and_b32_e32 v83, 0xffff0000, v76
	v_lshlrev_b32_e32 v84, 16, v77
	v_and_b32_e32 v85, 0xffff0000, v77
	s_waitcnt lgkmcnt(0)
	v_pk_mul_f32 v[76:77], v[80:81], v[82:83] op_sel_hi:[0,1]
	v_pk_mul_f32 v[82:83], v[80:81], v[84:85] op_sel_hi:[0,1]
	v_cvt_pk_bf16_f32 v76, v76, v77
	v_cvt_pk_bf16_f32 v77, v82, v83
	v_lshlrev_b32_e32 v82, 16, v78
	v_and_b32_e32 v83, 0xffff0000, v78
	v_pk_mul_f32 v[82:83], v[80:81], v[82:83] op_sel_hi:[0,1]
	v_cvt_pk_bf16_f32 v78, v82, v83
	v_lshlrev_b32_e32 v82, 16, v79
	v_and_b32_e32 v83, 0xffff0000, v79
	v_pk_mul_f32 v[80:81], v[80:81], v[82:83] op_sel_hi:[0,1]
	v_cvt_pk_bf16_f32 v79, v80, v81
	ds_write_b128 v205, v[76:79] offset:57344
	ds_read_b32 v76, v177
	v_lshlrev_b32_e32 v78, 16, v72
	v_and_b32_e32 v79, 0xffff0000, v72
	s_andn2_b64 vcc, exec, s[34:35]
	s_waitcnt lgkmcnt(0)
	v_pk_mul_f32 v[78:79], v[76:77], v[78:79] op_sel_hi:[0,1]
	v_cvt_pk_bf16_f32 v72, v78, v79
	v_lshlrev_b32_e32 v78, 16, v73
	v_and_b32_e32 v79, 0xffff0000, v73
	v_pk_mul_f32 v[78:79], v[76:77], v[78:79] op_sel_hi:[0,1]
	v_cvt_pk_bf16_f32 v73, v78, v79
	v_lshlrev_b32_e32 v78, 16, v74
	v_and_b32_e32 v79, 0xffff0000, v74
	v_pk_mul_f32 v[78:79], v[76:77], v[78:79] op_sel_hi:[0,1]
	v_cvt_pk_bf16_f32 v74, v78, v79
	v_lshlrev_b32_e32 v78, 16, v75
	v_and_b32_e32 v79, 0xffff0000, v75
	v_pk_mul_f32 v[76:77], v[76:77], v[78:79] op_sel_hi:[0,1]
	v_cvt_pk_bf16_f32 v75, v76, v77
	ds_write_b128 v223, v[72:75] offset:57344
	ds_read_b128 v[72:75], v203
	ds_read_b128 v[76:79], v203 offset:4352
	ds_read_b128 v[80:83], v203 offset:8704
	ds_read_b128 v[84:87], v203 offset:13056
	ds_read_b128 v[124:127], v203 offset:64
	ds_read_b128 v[128:131], v203 offset:4416
	ds_read_b128 v[132:135], v203 offset:8768
	ds_read_b128 v[136:139], v203 offset:13120
	ds_read_b128 v[140:143], v203 offset:128
	ds_read_b128 v[116:119], v203 offset:4480
	ds_read_b128 v[232:235], v203 offset:8832
	ds_read_b128 v[236:239], v203 offset:13184
	s_waitcnt lgkmcnt(11)
	v_mfma_f32_16x16x32_bf16 v[72:75], v[68:71], v[72:75], 0
	s_waitcnt lgkmcnt(10)
	v_mfma_f32_16x16x32_bf16 v[76:79], v[68:71], v[76:79], 0
	s_waitcnt lgkmcnt(9)
	v_mfma_f32_16x16x32_bf16 v[80:83], v[68:71], v[80:83], 0
	s_waitcnt lgkmcnt(8)
	v_mfma_f32_16x16x32_bf16 v[84:87], v[68:71], v[84:87], 0
	ds_read_b128 v[240:243], v203 offset:192
	ds_read_b128 v[244:247], v203 offset:4544
	ds_read_b128 v[248:251], v203 offset:8896
	ds_read_b128 v[92:95], v203 offset:13248
	s_waitcnt lgkmcnt(11)
	v_mfma_f32_16x16x32_bf16 v[72:75], v[64:67], v[124:127], v[72:75]
	s_waitcnt lgkmcnt(10)
	v_mfma_f32_16x16x32_bf16 v[76:79], v[64:67], v[128:131], v[76:79]
	s_waitcnt lgkmcnt(9)
	v_mfma_f32_16x16x32_bf16 v[80:83], v[64:67], v[132:135], v[80:83]
	s_waitcnt lgkmcnt(8)
	v_mfma_f32_16x16x32_bf16 v[84:87], v[64:67], v[136:139], v[84:87]
	s_waitcnt lgkmcnt(7)
	v_mfma_f32_16x16x32_bf16 v[72:75], v[60:63], v[140:143], v[72:75]
	s_waitcnt lgkmcnt(6)
	v_mfma_f32_16x16x32_bf16 v[76:79], v[60:63], v[116:119], v[76:79]
	s_waitcnt lgkmcnt(5)
	v_mfma_f32_16x16x32_bf16 v[80:83], v[60:63], v[232:235], v[80:83]
	s_waitcnt lgkmcnt(4)
	v_mfma_f32_16x16x32_bf16 v[84:87], v[60:63], v[236:239], v[84:87]
	s_waitcnt lgkmcnt(3)
	v_mfma_f32_16x16x32_bf16 v[60:63], v[56:59], v[240:243], v[72:75]
	s_waitcnt lgkmcnt(2)
	v_mfma_f32_16x16x32_bf16 v[64:67], v[56:59], v[244:247], v[76:79]
	s_waitcnt lgkmcnt(1)
	v_mfma_f32_16x16x32_bf16 v[80:83], v[56:59], v[248:251], v[80:83]
	s_waitcnt lgkmcnt(0)
	v_mfma_f32_16x16x32_bf16 v[56:59], v[56:59], v[92:95], v[84:87]
	s_cbranch_vccnz .LBB0_150
	s_nop 1
	v_cvt_pk_bf16_f32 v84, v148, v193
	v_cvt_pk_bf16_f32 v85, v195, v197
	v_cvt_pk_bf16_f32 v86, v112, v113
	v_cvt_pk_bf16_f32 v87, v114, v115
	ds_read_b64_tr_b16 v[124:125], v159 offset:0
	ds_read_b64_tr_b16 v[126:127], v159 offset:2816
	ds_read_b64_tr_b16 v[128:129], v159 offset:32
	ds_read_b64_tr_b16 v[130:131], v159 offset:2848
	ds_read_b64_tr_b16 v[132:133], v159 offset:64
	ds_read_b64_tr_b16 v[134:135], v159 offset:2880
	ds_read_b64_tr_b16 v[136:137], v159 offset:96
	ds_read_b64_tr_b16 v[138:139], v159 offset:2912
	s_andn2_b64 vcc, exec, s[42:43]
	s_cbranch_vccnz .Lib_s_last0
; template <bool ISM>
; __device__ void scan_item(const Params& p, int l, int item, unsigned char* lds) {
;     ...
;           SCAN_IB(0) SCAN_IB(1) SCAN_IB(2) SCAN_IB(3)
	ds_read_b64_tr_b16 v[140:141], v159 offset:5632
	ds_read_b64_tr_b16 v[142:143], v159 offset:8448
	ds_read_b64_tr_b16 v[116:117], v159 offset:5664
	ds_read_b64_tr_b16 v[118:119], v159 offset:8480
	ds_read_b64_tr_b16 v[232:233], v159 offset:5696
	ds_read_b64_tr_b16 v[234:235], v159 offset:8512
	ds_read_b64_tr_b16 v[236:237], v159 offset:5728
	ds_read_b64_tr_b16 v[238:239], v159 offset:8544
	v_cvt_pk_bf16_f32 v92, v104, v105
	v_cvt_pk_bf16_f32 v93, v106, v107
	v_cvt_pk_bf16_f32 v94, v108, v109
	v_cvt_pk_bf16_f32 v95, v110, v111
	s_waitcnt lgkmcnt(8)
	v_mfma_f32_16x16x32_bf16 v[68:71], v[84:87], v[124:127], 0
	v_mfma_f32_16x16x32_bf16 v[72:75], v[84:87], v[128:131], 0
	v_mfma_f32_16x16x32_bf16 v[76:79], v[84:87], v[132:135], 0
	v_mfma_f32_16x16x32_bf16 v[84:87], v[84:87], v[136:139], 0
	s_andn2_b64 vcc, exec, s[48:49]
	s_cbranch_vccnz .Lib_s_last1
	ds_read_b64_tr_b16 v[124:125], v159 offset:11264
	ds_read_b64_tr_b16 v[126:127], v159 offset:14080
	ds_read_b64_tr_b16 v[128:129], v159 offset:11296
	ds_read_b64_tr_b16 v[130:131], v159 offset:14112
	ds_read_b64_tr_b16 v[132:133], v159 offset:11328
	ds_read_b64_tr_b16 v[134:135], v159 offset:14144
	ds_read_b64_tr_b16 v[136:137], v159 offset:11360
	ds_read_b64_tr_b16 v[138:139], v159 offset:14176
	v_cvt_pk_bf16_f32 v104, v96, v97
	v_cvt_pk_bf16_f32 v105, v98, v99
	v_cvt_pk_bf16_f32 v106, v100, v101
	v_cvt_pk_bf16_f32 v107, v102, v103
	s_waitcnt lgkmcnt(8)
	v_mfma_f32_16x16x32_bf16 v[68:71], v[92:95], v[140:143], v[68:71]
	v_mfma_f32_16x16x32_bf16 v[72:75], v[92:95], v[116:119], v[72:75]
	v_mfma_f32_16x16x32_bf16 v[76:79], v[92:95], v[232:235], v[76:79]
	v_mfma_f32_16x16x32_bf16 v[84:87], v[92:95], v[236:239], v[84:87]
	s_andn2_b64 vcc, exec, s[54:55]
	s_cbranch_vccnz .Lib_s_last2
	ds_read_b64_tr_b16 v[140:141], v159 offset:16896
	ds_read_b64_tr_b16 v[142:143], v159 offset:19712
	ds_read_b64_tr_b16 v[116:117], v159 offset:16928
	ds_read_b64_tr_b16 v[118:119], v159 offset:19744
	ds_read_b64_tr_b16 v[232:233], v159 offset:16960
	ds_read_b64_tr_b16 v[234:235], v159 offset:19776
	ds_read_b64_tr_b16 v[236:237], v159 offset:16992
	ds_read_b64_tr_b16 v[238:239], v159 offset:19808
	v_cvt_pk_bf16_f32 v92, v120, v121
	v_cvt_pk_bf16_f32 v93, v122, v123
	v_cvt_pk_bf16_f32 v94, v88, v89
	v_cvt_pk_bf16_f32 v95, v90, v91
	s_waitcnt lgkmcnt(8)
	v_mfma_f32_16x16x32_bf16 v[68:71], v[104:107], v[124:127], v[68:71]
	v_mfma_f32_16x16x32_bf16 v[72:75], v[104:107], v[128:131], v[72:75]
	v_mfma_f32_16x16x32_bf16 v[76:79], v[104:107], v[132:135], v[76:79]
	v_mfma_f32_16x16x32_bf16 v[84:87], v[104:107], v[136:139], v[84:87]
	s_waitcnt lgkmcnt(0)
	v_mfma_f32_16x16x32_bf16 v[68:71], v[92:95], v[140:143], v[68:71]
	v_mfma_f32_16x16x32_bf16 v[72:75], v[92:95], v[116:119], v[72:75]
	v_mfma_f32_16x16x32_bf16 v[76:79], v[92:95], v[232:235], v[76:79]
	v_mfma_f32_16x16x32_bf16 v[84:87], v[92:95], v[236:239], v[84:87]
	s_branch .LBB0_118
.Lib_s_last0:
	s_waitcnt lgkmcnt(0)
	s_nop 0
	v_mfma_f32_16x16x32_bf16 v[68:71], v[84:87], v[124:127], 0
	v_mfma_f32_16x16x32_bf16 v[72:75], v[84:87], v[128:131], 0
	v_mfma_f32_16x16x32_bf16 v[76:79], v[84:87], v[132:135], 0
	v_mfma_f32_16x16x32_bf16 v[84:87], v[84:87], v[136:139], 0
	s_branch .LBB0_118
.Lib_s_last1:
	s_waitcnt lgkmcnt(0)
	s_nop 0
	v_mfma_f32_16x16x32_bf16 v[68:71], v[92:95], v[140:143], v[68:71]
	v_mfma_f32_16x16x32_bf16 v[72:75], v[92:95], v[116:119], v[72:75]
	v_mfma_f32_16x16x32_bf16 v[76:79], v[92:95], v[232:235], v[76:79]
	v_mfma_f32_16x16x32_bf16 v[84:87], v[92:95], v[236:239], v[84:87]
	s_branch .LBB0_118
.Lib_s_last2:
	s_waitcnt lgkmcnt(0)
	s_nop 0
	v_mfma_f32_16x16x32_bf16 v[68:71], v[104:107], v[124:127], v[68:71]
	v_mfma_f32_16x16x32_bf16 v[72:75], v[104:107], v[128:131], v[72:75]
	v_mfma_f32_16x16x32_bf16 v[76:79], v[104:107], v[132:135], v[76:79]
	v_mfma_f32_16x16x32_bf16 v[84:87], v[104:107], v[136:139], v[84:87]
	s_branch .LBB0_118

; template <bool ISM>
; __device__ void scan_item(const Params& p, int l, int item, unsigned char* lds) {
;     ...
;     const unsigned trK = ldsb + LS_K + (unsigned)(((fq * 8 + trq) * LDK + 16 * wid + 4 * trp) * 2);
;     const unsigned trVw = ldsb + LS_VW + (unsigned)(((fq * 8 + trq) * LDV + 4 * trp) * 2);
;     const unsigned trV = ldsb + LS_V + (unsigned)(((fq * 4 + trq) * LDV + 4 * trp) * 2);
;     const float Dh = ISM ? 0.f : p.d_skip[l * 32 + h];
;     const u16* __restrict__ gQKX = p.QKX; const u16* __restrict__ gP = p.P; const float* __restrict__ gG2 = p.G2;
;     const int gcol = ISM ? (dir * 8 + h) * 3 : 48 + (dir * 32 + h) * 2;
;     __syncthreads();
;     for (int i = tid; i < 128 * 24; i += 512) { const int r = i / 24, cc = 64 + i % 24; Vs[r * LDV + cc] = (ISM && cc == 64) ? (u16)0x3F80 : (u16)0; Vw[r * LDV + cc] = 0; }
;     for (int i = tid; i < 80 * LDK; i += 512) CT[i] = 0;
;     f32x4 st[NT];
; #pragma unroll
;     for (int m = 0; m < NT; ++m) st[m] = (f32x4){0.f, 0.f, 0.f, 0.f};
;     float m_prev = 0.f;
;     unsigned qo, ko[4], vo[2], go, ge, oo[4];
;     bf16x8 qf[4]; u32x4 kr[4]; u32x4 vr[2]; f32x3 gv = {0.f, 0.f, 0.f}; float e0 = 0.f, e1 = 0.f;
;     ...
;     SCAN_PTRS(0); SCAN_LOAD();
;     const int dr_ctx = dir ? -128 : 128, dr_lat = ISM ? dr_ctx : (dir ? -1 : 1);
;     __syncthreads();
.LBB0_161:
	s_or_b64 exec, exec, s[4:5]
	v_or_b32_e32 v37, s9, v153
	s_and_b64 s[4:5], vcc, exec
	s_movk_i32 s14, 0x3400
	v_sub_u32_e32 v38, 0xff, v37
	s_cselect_b32 s13, s14, 0x800
	s_add_i32 s4, s10, s3
	v_cndmask_b32_e32 v38, v38, v37, vcc
	s_mulk_i32 s4, 0xb0
	v_or_b32_e32 v36, s12, v19
	v_add_u32_e32 v38, s3, v38
	s_add_i32 s10, s4, s67
	v_mad_u64_u32 v[200:201], s[4:5], v38, s13, v[36:37]
	v_or_b32_e32 v38, 1, v37
	v_sub_u32_e32 v39, 0xff, v38
	v_cndmask_b32_e32 v39, v39, v38, vcc
	v_add_u32_e32 v39, s3, v39
	v_mad_u64_u32 v[198:199], s[4:5], v39, s13, v[36:37]
	v_or_b32_e32 v39, 2, v37
	v_sub_u32_e32 v40, 0xff, v39
	v_cndmask_b32_e32 v40, v40, v39, vcc
	v_add_u32_e32 v40, s3, v40
	v_mad_u64_u32 v[196:197], s[4:5], v40, s13, v[36:37]
	v_or_b32_e32 v40, 3, v37
	v_sub_u32_e32 v41, 0xff, v40
	s_lshl_b32 s11, s11, 13
	v_cndmask_b32_e32 v41, v41, v40, vcc
	s_add_i32 s90, s10, 0x5750
	v_add_u32_e32 v41, s3, v41
	s_and_b64 s[4:5], vcc, exec
	v_readlane_b32 s3, v254, 30
	v_mad_u64_u32 v[194:195], s[4:5], v41, s13, v[36:37]
	s_cselect_b32 s29, s71, s3
	v_readlane_b32 s3, v254, 29
	s_mov_b32 s91, s36
	s_cselect_b32 s28, s70, s3
	s_lshl_b64 s[4:5], s[90:91], 2
	s_add_u32 s4, s74, s4
	s_addc_u32 s5, s75, s5
	global_load_dword v195, v149, s[4:5]
	global_load_dword v229, v149, s[4:5] offset:8
	v_lshlrev_b32_e32 v41, 2, v20
	v_and_b32_e32 v42, 12, v41
	v_add_u32_e32 v28, v28, v42
	v_readlane_b32 s3, v254, 4
	s_and_b64 s[4:5], vcc, exec
	s_mov_b32 s4, 0x1a0000
	v_lshl_add_u32 v161, v28, 1, s3
	v_add_u32_e32 v28, v29, v42
	v_readlane_b32 s3, v254, 5
	s_cselect_b32 s66, s4, 0xfffc0000
	s_movk_i32 s10, 0xb0
	v_lshl_add_u32 v163, v28, 1, s3
	v_sub_u32_e32 v28, 0x1fff, v31
	s_cselect_b32 s3, s76, 0xffffff80
	s_bitset1_b32 s11, 9
	v_cndmask_b32_e32 v28, v28, v31, vcc
	v_add_u32_e32 v28, s11, v28
	v_mul_lo_u32 v28, v28, s92
	s_and_b64 s[4:5], vcc, exec
	v_or_b32_e32 v223, v28, v32
	v_xor_b32_e32 v28, 0x1fff, v35
	s_movk_i32 s4, 0x7f
	v_cndmask_b32_e32 v28, v28, v35, vcc
	s_cselect_b32 s4, s4, 0x1f80
	v_add_u32_e32 v28, s11, v28
	s_add_i32 s4, s4, s11
	v_mul_lo_u32 v28, v28, s10
	s_mulk_i32 s4, 0xb0
	v_add_u32_e32 v224, s67, v28
	s_add_i32 s67, s67, s4
	s_cmp_gt_i32 s16, -1
	s_cselect_b64 s[76:77], -1, 0
	s_cmp_gt_i32 s16, 1
	s_cselect_b64 s[78:79], -1, 0
	s_cmp_lt_i32 s16, 2
	s_cselect_b64 s[80:81], -1, 0
	s_cmp_gt_i32 s16, 3
	s_cselect_b64 s[82:83], -1, 0
	s_cmp_lt_i32 s16, 4
	s_cselect_b64 s[84:85], -1, 0
	s_cmp_gt_i32 s16, 5
	v_readlane_b32 s12, v254, 6
	v_readlane_b32 s15, v254, 7
	v_readlane_b32 s17, v254, 8
	v_readlane_b32 s18, v254, 9
	v_readlane_b32 s19, v254, 10
	s_cselect_b64 s[86:87], -1, 0
	s_cmp_lt_i32 s16, 6
	v_add_u32_e32 v165, s12, v41
	v_add_u32_e32 v167, s15, v41
	v_add_u32_e32 v169, s17, v41
	v_add_u32_e32 v171, s18, v41
	v_add_u32_e32 v173, s19, v41
	v_mul_lo_u32 v41, v20, s10
	v_readlane_b32 s5, v254, 3
	s_cselect_b64 s[88:89], -1, 0
	v_and_b32_e32 v228, 48, v20
	s_lshl_b32 s4, s9, 1
	v_sub_u32_e32 v20, 0x1fff, v24
	s_add_i32 s4, s5, s4
	v_cndmask_b32_e32 v20, v20, v24, vcc
	v_lshlrev_b32_e32 v23, 1, v23
	v_lshl_add_u32 v45, v19, 1, s4
	s_movk_i32 s4, 0x110
	v_add_u32_e32 v20, s11, v20
	v_add_u32_e32 v44, s5, v23
	v_mul_lo_u32 v46, v24, s4
	v_mul_lo_u32 v47, v25, s4
	v_mul_lo_u32 v48, v26, s4
	v_mul_lo_u32 v49, v27, s4
	v_mad_u64_u32 v[174:175], s[4:5], v20, s92, v[16:17]
	v_sub_u32_e32 v20, 0x1fff, v25
	v_cndmask_b32_e32 v20, v20, v25, vcc
	v_add_u32_e32 v20, s11, v20
	v_mad_u64_u32 v[176:177], s[4:5], v20, s92, v[16:17]
	v_sub_u32_e32 v20, 0x1fff, v26
	v_cndmask_b32_e32 v20, v20, v26, vcc
	v_add_u32_e32 v20, s11, v20
	v_mad_u64_u32 v[178:179], s[4:5], v20, s92, v[16:17]
	v_sub_u32_e32 v20, 0x1fff, v27
	v_cndmask_b32_e32 v20, v20, v27, vcc
	v_add_u32_e32 v20, s11, v20
	v_mad_u64_u32 v[180:181], s[4:5], v20, s92, v[16:17]
	v_sub_u32_e32 v16, 0x1fff, v21
	v_cndmask_b32_e32 v16, v16, v21, vcc
	v_add_u32_e32 v16, s11, v16
	v_mad_u64_u32 v[182:183], s[4:5], v16, s14, v[18:19]
	v_sub_u32_e32 v16, 0x1fff, v22
	v_cndmask_b32_e32 v16, v16, v22, vcc
	v_add_u32_e32 v16, s11, v16
	v_mad_u64_u32 v[184:185], s[4:5], v16, s14, v[18:19]
	v_sub_u32_e32 v16, 0x1fff, v37
	s_cmp_lt_i32 s16, 1
	v_cndmask_b32_e32 v16, v16, v37, vcc
	s_cselect_b64 s[92:93], -1, 0
	s_cmp_lt_i32 s16, 3
	v_add_u32_e32 v16, s11, v16
	s_cselect_b64 s[94:95], -1, 0
	s_cmp_eq_u32 s16, 2
	v_mad_u64_u32 v[186:187], s[4:5], v16, s13, v[36:37]
	v_sub_u32_e32 v16, 0x1fff, v38
	s_cselect_b64 s[96:97], -1, 0
	s_cmp_lt_i32 s16, 5
	v_cndmask_b32_e32 v16, v16, v38, vcc
	s_cselect_b64 s[98:99], -1, 0
	s_cmp_eq_u32 s16, 4
	v_add_u32_e32 v16, s11, v16
	s_cselect_b64 s[48:49], -1, 0
	s_cmp_lt_i32 s16, 7
	v_mad_u64_u32 v[188:189], s[4:5], v16, s13, v[36:37]
	v_sub_u32_e32 v16, 0x1fff, v39
	s_cselect_b64 s[52:53], -1, 0
	s_cmp_eq_u32 s16, 6
	v_cndmask_b32_e32 v16, v16, v39, vcc
	s_cselect_b64 s[54:55], -1, 0
	s_cmp_lt_u32 s8, 64
	v_add_u32_e32 v16, s11, v16
	s_cselect_b64 s[56:57], -1, 0
	s_cmp_eq_u32 s16, 1
	v_mad_u64_u32 v[190:191], s[4:5], v16, s13, v[36:37]
	v_sub_u32_e32 v16, 0x1fff, v40
	s_cselect_b64 s[58:59], -1, 0
	s_cmp_eq_u32 s16, 3
	v_cndmask_b32_e32 v16, v16, v40, vcc
	s_cselect_b64 s[30:31], -1, 0
	s_cmp_eq_u32 s16, 5
	v_or_b32_e32 v43, s9, v42
	v_add_u32_e32 v16, s11, v16
	s_cselect_b64 s[44:45], -1, 0
	s_cmp_lt_i32 s16, 8
	v_add_u32_e32 v30, v43, v30
	v_lshl_add_u32 v42, v33, 1, 0
	v_lshl_add_u32 v43, v34, 1, 0
	v_mul_lo_u32 v50, v21, s10
	v_mul_lo_u32 v51, v22, s10
	v_mad_u64_u32 v[192:193], s[4:5], v16, s13, v[36:37]
	v_mul_u32_u24_e32 v175, 0x110, v19
	v_or_b32_e32 v177, 2, v153
	v_or_b32_e32 v179, 3, v153
	s_cselect_b64 s[42:43], -1, 0
	s_cmp_eq_u32 s16, 7
	v_lshlrev_b32_e32 v16, 2, v37
	v_mul_u32_u24_e32 v36, 0x440, v17
	v_lshl_add_u32 v159, v30, 1, 0
	s_mul_i32 s69, s3, 0x1400
	s_mul_i32 s91, s3, 0x3400
	s_mulk_i32 s3, 0xb0
	v_add_u32_e32 v225, 0, v23
	v_lshl_add_u32 v226, v31, 2, s15
	v_lshl_add_u32 v227, v153, 2, s12
	v_cmp_gt_u32_e64 s[8:9], v153, v19
	v_cmp_lt_u32_e64 s[10:11], v153, v19
	v_cmp_gt_u32_e64 s[12:13], v177, v19
	v_cmp_gt_u32_e64 s[14:15], v179, v19
	s_cselect_b64 s[34:35], -1, 0
	v_lshl_add_u32 v181, v21, 2, s18
	v_lshl_add_u32 v183, v22, 2, s18
	v_add_u32_e32 v185, s17, v16
	v_add_u32_e32 v187, s19, v16
	v_or_b32_e32 v189, 1, v153
	s_movk_i32 s63, 0x41
	v_mov_b32_e32 v191, 0
	v_mov_b32_e32 v16, 0
	v_mov_b32_e32 v17, 0
	v_mov_b32_e32 v18, 0
	v_mov_b32_e32 v19, 0
	v_mov_b32_e32 v20, 0
	v_mov_b32_e32 v21, 0
	v_mov_b32_e32 v22, 0
	v_mov_b32_e32 v23, 0
	v_mov_b32_e32 v24, 0
	v_mov_b32_e32 v25, 0
	v_mov_b32_e32 v26, 0
	v_mov_b32_e32 v27, 0
	v_mov_b32_e32 v28, 0
	v_mov_b32_e32 v29, 0
	v_mov_b32_e32 v30, 0
	v_mov_b32_e32 v31, 0
	v_mov_b32_e32 v32, 0
	v_mov_b32_e32 v33, 0
	v_mov_b32_e32 v34, 0
	v_mov_b32_e32 v35, 0
	v_add_u32_e32 v193, v42, v46
	v_add_u32_e32 v230, v42, v47
	v_add_u32_e32 v231, v42, v48
	v_add_u32_e32 v232, v42, v49
	v_add_u32_e32 v233, 0, v41
	v_add_u32_e32 v234, v44, v175
	v_add_u32_e32 v235, v45, v36
	v_add_u32_e32 v236, v43, v50
	v_add_u32_e32 v237, v43, v51
	s_waitcnt lgkmcnt(0)
	s_barrier
; template <bool ISM>
; __device__ void scan_item(const Params& p, int l, int item, unsigned char* lds) {
;     ...
;     SCAN_PTRS(0); SCAN_LOAD();
;     const int dr_ctx = dir ? -128 : 128, dr_lat = ISM ? dr_ctx : (dir ? -1 : 1);
;     __syncthreads();
; #pragma unroll 1
;     for (int c = 0; c < 66; ++c) {
	s_waitcnt vmcnt(0)
	s_branch .LBB0_163

; template <bool ISM>
; __device__ void scan_item(const Params& p, int l, int item, unsigned char* lds) {
;     ...
;         for (int rep = 0; rep < 4; ++rep) { const int idx = rep * 512 + tid; *(u32x4*)(Ks + (idx >> 4) * LDK + (idx & 15) * 8) = kr[rep]; }
; #pragma unroll
;         for (int rep = 0; rep < 2; ++rep) { const int idx = rep * 512 + tid; *(u32x4*)(Vs + (idx >> 3) * LDV + (idx & 7) * 8) = vr[rep]; }
;         float decay;
;         if (ISM) {
;             const float Ml = fmaxf(m_prev, e1);
;             if (tid < 128) { const float M = fmaxf(m_prev, gv[2]);
;                 f_c[tid] = gv[1] * L2E; f_r[tid] = M * L2E; f_wi[tid] = __expf(m_prev - M); f_ws[tid] = __expf(gv[1] - Ml); f_em[tid] = __expf(-(gv[0] + M)); }
;             decay = __expf(m_prev - Ml); m_prev = e0 + Ml;
.LBB0_163:
	s_waitcnt vmcnt(16)
	v_max_f32_e32 v37, v229, v229
	v_max_f32_e32 v36, v191, v191
	v_max_f32_e32 v197, v36, v37
	ds_write_b128 v193, v[0:3]
	ds_write_b128 v230, v[4:7]
	ds_write_b128 v231, v[8:11]
	ds_write_b128 v232, v[12:15]
	ds_write_b128 v236, v[80:83] offset:34816
	ds_write_b128 v237, v[76:79] offset:34816
	s_and_saveexec_b64 s[4:5], s[6:7]
	s_cbranch_execz .LBB0_165
	v_max_f32_e32 v37, v152, v152
	v_max_f32_e32 v36, v36, v37
	v_mul_f32_e32 v37, 0x3fb8aa3b, v151
	ds_write_b32 v165, v37
	v_mul_f32_e32 v37, 0x3fb8aa3b, v36
	ds_write_b32 v167, v37
	v_sub_f32_e32 v37, v191, v36
	v_mul_f32_e32 v37, 0x3fb8aa3b, v37
	v_exp_f32_e32 v37, v37
	v_add_f32_e32 v36, v150, v36
	v_mul_f32_e32 v36, 0xbfb8aa3b, v36
	v_exp_f32_e32 v36, v36
	ds_write_b32 v169, v37
	v_sub_f32_e32 v37, v151, v197
	v_mul_f32_e32 v37, 0x3fb8aa3b, v37
	v_exp_f32_e32 v37, v37
	ds_write_b32 v173, v36
	ds_write_b32 v171, v37

; template <bool ISM>
; __device__ void scan_item(const Params& p, int l, int item, unsigned char* lds) {
;     ...
;           for (int ksd = 0; ksd < 4; ++ksd) { bf16x8 bfr[NT];
; #pragma unroll
;               for (int n = 0; n < NT; ++n) bfr[n] = *(const bf16x8*)(CT + (n * 16 + fr) * LDK + ksd * 32 + fq * 8);
; #pragma unroll
;               for (int n = 0; n < NT; ++n) ia[n] = __builtin_amdgcn_mfma_f32_16x16x32_bf16(qc[ksd], bfr[n], ia[n], 0, 0, 0); }
;     ...
;           SCAN_IB(0) SCAN_IB(1) SCAN_IB(2) SCAN_IB(3)
.LBB0_238:
	s_or_b64 exec, exec, s[4:5]
	ds_read_b128 v[80:83], v234
	ds_read_b128 v[84:87], v234 offset:4352
	ds_read_b128 v[88:91], v234 offset:8704
	ds_read_b128 v[76:79], v234 offset:13056
	ds_read_b128 v[92:95], v234 offset:17408
	ds_read_b128 v[128:131], v234 offset:64
	ds_read_b128 v[132:135], v234 offset:4416
	ds_read_b128 v[136:139], v234 offset:8768
	ds_read_b128 v[140:143], v234 offset:13120
	ds_read_b128 v[144:147], v234 offset:17472
	ds_read_b128 v[244:247], v234 offset:128
	ds_read_b128 v[248:251], v234 offset:4480
	s_andn2_b64 vcc, exec, s[76:77]
	s_waitcnt lgkmcnt(11)
	v_mfma_f32_16x16x32_bf16 v[80:83], v[72:75], v[80:83], 0
	s_waitcnt lgkmcnt(10)
	v_mfma_f32_16x16x32_bf16 v[84:87], v[72:75], v[84:87], 0
	s_waitcnt lgkmcnt(9)
	v_mfma_f32_16x16x32_bf16 v[88:91], v[72:75], v[88:91], 0
	s_waitcnt lgkmcnt(8)
	v_mfma_f32_16x16x32_bf16 v[76:79], v[72:75], v[76:79], 0
	s_waitcnt lgkmcnt(7)
	v_mfma_f32_16x16x32_bf16 v[92:95], v[72:75], v[92:95], 0
	s_waitcnt lgkmcnt(6)
	v_mfma_f32_16x16x32_bf16 v[80:83], v[68:71], v[128:131], v[80:83]
	ds_read_b128 v[128:131], v234 offset:8832
	s_waitcnt lgkmcnt(6)
	v_mfma_f32_16x16x32_bf16 v[84:87], v[68:71], v[132:135], v[84:87]
	ds_read_b128 v[132:135], v234 offset:13184
	s_waitcnt lgkmcnt(6)
	v_mfma_f32_16x16x32_bf16 v[88:91], v[68:71], v[136:139], v[88:91]
	ds_read_b128 v[136:139], v234 offset:17536
	s_waitcnt lgkmcnt(6)
	v_mfma_f32_16x16x32_bf16 v[76:79], v[68:71], v[140:143], v[76:79]
	ds_read_b128 v[140:143], v234 offset:192
	s_waitcnt lgkmcnt(6)
	v_mfma_f32_16x16x32_bf16 v[92:95], v[68:71], v[144:147], v[92:95]
	ds_read_b128 v[144:147], v234 offset:4544
	s_waitcnt lgkmcnt(6)
	v_mfma_f32_16x16x32_bf16 v[80:83], v[64:67], v[244:247], v[80:83]
	ds_read_b128 v[244:247], v234 offset:8896
	s_waitcnt lgkmcnt(6)
	v_mfma_f32_16x16x32_bf16 v[84:87], v[64:67], v[248:251], v[84:87]
	ds_read_b128 v[248:251], v234 offset:13248
	s_waitcnt lgkmcnt(6)
	v_mfma_f32_16x16x32_bf16 v[88:91], v[64:67], v[128:131], v[88:91]
	ds_read_b128 v[128:131], v234 offset:17600
	s_waitcnt lgkmcnt(6)
	v_mfma_f32_16x16x32_bf16 v[76:79], v[64:67], v[132:135], v[76:79]
	s_waitcnt lgkmcnt(5)
	v_mfma_f32_16x16x32_bf16 v[92:95], v[64:67], v[136:139], v[92:95]
	s_waitcnt lgkmcnt(4)
	v_mfma_f32_16x16x32_bf16 v[64:67], v[60:63], v[140:143], v[80:83]
	s_waitcnt lgkmcnt(3)
	v_mfma_f32_16x16x32_bf16 v[68:71], v[60:63], v[144:147], v[84:87]
	s_waitcnt lgkmcnt(2)
	v_mfma_f32_16x16x32_bf16 v[72:75], v[60:63], v[244:247], v[88:91]
	s_waitcnt lgkmcnt(1)
	v_mfma_f32_16x16x32_bf16 v[76:79], v[60:63], v[248:251], v[76:79]
	s_waitcnt lgkmcnt(0)
	v_mfma_f32_16x16x32_bf16 v[92:95], v[60:63], v[128:131], v[92:95]
	s_cbranch_vccnz .LBB0_245
	v_cvt_pk_bf16_f32 v80, v202, v203
	v_cvt_pk_bf16_f32 v81, v204, v205
	v_cvt_pk_bf16_f32 v82, v124, v125
	v_cvt_pk_bf16_f32 v83, v126, v127
	ds_read_b64_tr_b16 v[128:129], v163 offset:0
	ds_read_b64_tr_b16 v[130:131], v163 offset:2816
	ds_read_b64_tr_b16 v[132:133], v163 offset:32
	ds_read_b64_tr_b16 v[134:135], v163 offset:2848
	ds_read_b64_tr_b16 v[136:137], v163 offset:64
	ds_read_b64_tr_b16 v[138:139], v163 offset:2880
	ds_read_b64_tr_b16 v[140:141], v163 offset:96
	ds_read_b64_tr_b16 v[142:143], v163 offset:2912
	s_andn2_b64 vcc, exec, s[78:79]
	s_cbranch_vccnz .Lib_m_last0
	ds_read_b64_tr_b16 v[144:145], v163 offset:5632
	ds_read_b64_tr_b16 v[146:147], v163 offset:8448
	ds_read_b64_tr_b16 v[244:245], v163 offset:5664
	ds_read_b64_tr_b16 v[246:247], v163 offset:8480
	ds_read_b64_tr_b16 v[248:249], v163 offset:5696
	ds_read_b64_tr_b16 v[250:251], v163 offset:8512
	ds_read_b64_tr_b16 v[124:125], v163 offset:5728
	ds_read_b64_tr_b16 v[126:127], v163 offset:8544
	v_cvt_pk_bf16_f32 v116, v116, v117
	v_cvt_pk_bf16_f32 v117, v118, v119
	v_cvt_pk_bf16_f32 v118, v112, v113
	v_cvt_pk_bf16_f32 v119, v114, v115
	s_waitcnt lgkmcnt(8)
	v_mfma_f32_16x16x32_bf16 v[84:87], v[80:83], v[128:131], 0
	v_mfma_f32_16x16x32_bf16 v[88:91], v[80:83], v[132:135], 0
	v_mfma_f32_16x16x32_bf16 v[60:63], v[80:83], v[136:139], 0
	v_mfma_f32_16x16x32_bf16 v[80:83], v[80:83], v[140:143], 0
	s_andn2_b64 vcc, exec, s[82:83]
	s_cbranch_vccnz .Lib_m_last1
	ds_read_b64_tr_b16 v[128:129], v163 offset:11264
	ds_read_b64_tr_b16 v[130:131], v163 offset:14080
	ds_read_b64_tr_b16 v[132:133], v163 offset:11296
	ds_read_b64_tr_b16 v[134:135], v163 offset:14112
	ds_read_b64_tr_b16 v[136:137], v163 offset:11328
	ds_read_b64_tr_b16 v[138:139], v163 offset:14144
	ds_read_b64_tr_b16 v[140:141], v163 offset:11360
	ds_read_b64_tr_b16 v[142:143], v163 offset:14176
	v_cvt_pk_bf16_f32 v104, v104, v105
	v_cvt_pk_bf16_f32 v105, v106, v107
	v_cvt_pk_bf16_f32 v106, v100, v101
	v_cvt_pk_bf16_f32 v107, v102, v103
	s_waitcnt lgkmcnt(8)
	v_mfma_f32_16x16x32_bf16 v[84:87], v[116:119], v[144:147], v[84:87]
	v_mfma_f32_16x16x32_bf16 v[88:91], v[116:119], v[244:247], v[88:91]
	v_mfma_f32_16x16x32_bf16 v[60:63], v[116:119], v[248:251], v[60:63]
	v_mfma_f32_16x16x32_bf16 v[80:83], v[116:119], v[124:127], v[80:83]
	s_andn2_b64 vcc, exec, s[86:87]
	s_cbranch_vccnz .Lib_m_last2
	ds_read_b64_tr_b16 v[144:145], v163 offset:16896
	ds_read_b64_tr_b16 v[146:147], v163 offset:19712
	ds_read_b64_tr_b16 v[244:245], v163 offset:16928
	ds_read_b64_tr_b16 v[246:247], v163 offset:19744
	ds_read_b64_tr_b16 v[248:249], v163 offset:16960
	ds_read_b64_tr_b16 v[250:251], v163 offset:19776
	ds_read_b64_tr_b16 v[124:125], v163 offset:16992
	ds_read_b64_tr_b16 v[126:127], v163 offset:19808
	v_cvt_pk_bf16_f32 v96, v96, v97
	v_cvt_pk_bf16_f32 v97, v98, v99
	v_cvt_pk_bf16_f32 v98, v108, v109
	v_cvt_pk_bf16_f32 v99, v110, v111
	s_waitcnt lgkmcnt(8)
	v_mfma_f32_16x16x32_bf16 v[84:87], v[104:107], v[128:131], v[84:87]
	v_mfma_f32_16x16x32_bf16 v[88:91], v[104:107], v[132:135], v[88:91]
	v_mfma_f32_16x16x32_bf16 v[60:63], v[104:107], v[136:139], v[60:63]
	v_mfma_f32_16x16x32_bf16 v[80:83], v[104:107], v[140:143], v[80:83]
	s_waitcnt lgkmcnt(0)
	v_mfma_f32_16x16x32_bf16 v[84:87], v[96:99], v[144:147], v[84:87]
	v_mfma_f32_16x16x32_bf16 v[88:91], v[96:99], v[244:247], v[88:91]
	v_mfma_f32_16x16x32_bf16 v[60:63], v[96:99], v[248:251], v[60:63]
	v_mfma_f32_16x16x32_bf16 v[80:83], v[96:99], v[124:127], v[80:83]
	s_branch .LBB0_162
; template <bool ISM>
; __device__ void scan_item(const Params& p, int l, int item, unsigned char* lds) {
;     ...
;           SCAN_IB(0) SCAN_IB(1) SCAN_IB(2) SCAN_IB(3)
.Lib_m_last0:
	s_waitcnt lgkmcnt(0)
	s_nop 0
	v_mfma_f32_16x16x32_bf16 v[84:87], v[80:83], v[128:131], 0
	v_mfma_f32_16x16x32_bf16 v[88:91], v[80:83], v[132:135], 0
	v_mfma_f32_16x16x32_bf16 v[60:63], v[80:83], v[136:139], 0
	v_mfma_f32_16x16x32_bf16 v[80:83], v[80:83], v[140:143], 0
	s_branch .LBB0_162
.Lib_m_last1:
	s_waitcnt lgkmcnt(0)
	s_nop 0
	v_mfma_f32_16x16x32_bf16 v[84:87], v[116:119], v[144:147], v[84:87]
	v_mfma_f32_16x16x32_bf16 v[88:91], v[116:119], v[244:247], v[88:91]
	v_mfma_f32_16x16x32_bf16 v[60:63], v[116:119], v[248:251], v[60:63]
	v_mfma_f32_16x16x32_bf16 v[80:83], v[116:119], v[124:127], v[80:83]
	s_branch .LBB0_162
.Lib_m_last2:
	s_waitcnt lgkmcnt(0)
	s_nop 0
	v_mfma_f32_16x16x32_bf16 v[84:87], v[104:107], v[128:131], v[84:87]
	v_mfma_f32_16x16x32_bf16 v[88:91], v[104:107], v[132:135], v[88:91]
	v_mfma_f32_16x16x32_bf16 v[60:63], v[104:107], v[136:139], v[60:63]
	v_mfma_f32_16x16x32_bf16 v[80:83], v[104:107], v[140:143], v[80:83]
	s_branch .LBB0_162

; #define TIDX tid_()
; #define BIDX bid_()
; #define GDIM gdim_()
; __device__ void phase_ln(const Params& p, int l) {
;     const int wid = TIDX >> 6, lane = TIDX & 63;
;     const int nw = GDIM * 8;
;     const bool fin = (l == DEPTH);
;     for (int row = BIDX * 8 + wid; row < MROWS; row += nw) {
;         const bool isctx = row < CTXROWS;
;         if (fin && isctx) continue;
;         const int b = isctx ? (row >> 8) : ((row - CTXROWS) >> 13);
;         float* rw = isctx ? p.RC + (size_t)row * D : p.out + (size_t)(row - CTXROWS) * D;
;         const float* src = (l == 0) ? (isctx ? p.ctx + (size_t)row * D : p.x + (size_t)(row - CTXROWS) * D) : rw;
;         f32x4 v[8];
; #pragma unroll
;         for (int i = 0; i < 8; ++i) v[i] = *(const f32x4*)(src + i * 256 + lane * 4);
;         float mean, rstd;
;         if (l > 0) {
;             row_stats(v, mean, rstd);
;             const float* g = p.ln_g + (size_t)(l - 1) * D; const float* bb = p.ln_b + (size_t)(l - 1) * D;
; #pragma unroll
;             for (int i = 0; i < 8; ++i) { const f32x4 gv = *(const f32x4*)(g + i * 256 + lane * 4), bv = *(const f32x4*)(bb + i * 256 + lane * 4);
.LBB0_341:
	s_andn2_b64 vcc, exec, s[56:57]
	s_cbranch_vccnz .LBB0_437
	s_load_dwordx2 s[4:5], s[0:1], 0xa8
	s_waitcnt lgkmcnt(0)
	s_load_dwordx2 s[10:11], s[0:1], 0
	s_waitcnt lgkmcnt(0)
	s_load_dwordx2 s[6:7], s[0:1], 16
	s_waitcnt lgkmcnt(0)
	s_load_dwordx2 s[28:29], s[0:1], 0x90
	s_waitcnt lgkmcnt(0)
	s_load_dwordx2 s[8:9], s[0:1], 0x98
	s_waitcnt lgkmcnt(0)
	s_waitcnt vmcnt(0)
	v_mov_b32_e32 v0, v206
	s_load_dwordx2 s[12:13], s[0:1], 0xa0
	s_waitcnt lgkmcnt(0)
	s_waitcnt lgkmcnt(0)
	s_mov_b32 s18, s59
	v_ashrrev_i32_e32 v1, 6, v0
	v_mov_b32_e32 v0, v206
	s_mov_b32 s3, s2
	s_nop 0
	v_lshl_add_u32 v32, s3, 3, v1
	s_movk_i32 s3, 0x4200
	v_cmp_gt_i32_e32 vcc, s3, v32
	s_and_saveexec_b64 s[14:15], vcc
	s_cbranch_execz .LBB0_354
	s_add_u32 s3, s4, 0x32454000
	s_addc_u32 s37, s5, 0
	s_add_u32 s16, s4, 0x32430000
	v_readlane_b32 s24, v254, 18
	s_addc_u32 s17, s5, 0
	s_lshl_b32 s18, s18, 3
	s_add_i32 s19, s24, -13
	s_cmp_lt_u32 s19, 6
	s_cselect_b64 s[20:21], -1, 0
	s_cmp_gt_u32 s19, 5
	s_cselect_b64 s[22:23], -1, 0
	s_add_i32 s19, s24, 4
	s_cmp_lt_u32 s19, 11
	v_readlane_b32 s19, v254, 21
	v_readlane_b32 s30, v254, 19
	s_cselect_b64 s[24:25], -1, 0
	s_cmp_gt_i32 s19, 5
	v_readlane_b32 s31, v254, 20
	s_cselect_b64 s[26:27], -1, 0
	s_mov_b32 s34, s30
	s_add_i32 s30, s30, -1
	s_mov_b32 s31, s36
	s_lshl_b64 s[30:31], s[30:31], 13
	s_add_u32 s28, s28, s30
	v_lshlrev_b32_e32 v1, 2, v0
	s_addc_u32 s29, s29, s31
	v_and_b32_e32 v34, 0xfc, v1
	s_add_u32 s8, s8, s30
	s_addc_u32 s9, s9, s31
	v_lshlrev_b32_e32 v148, 2, v34
	v_lshl_add_u64 v[36:37], s[28:29], 0, v[148:149]
	v_lshl_add_u64 v[38:39], s[8:9], 0, v[148:149]
	s_mov_b64 s[8:9], 0x1000
	v_lshl_add_u64 v[40:41], v[36:37], 0, s[8:9]
	v_lshl_add_u64 v[42:43], v[38:39], 0, s[8:9]
	s_mov_b64 s[8:9], 0x1400
	v_ashrrev_i32_e32 v33, 31, v32
	v_lshl_add_u64 v[44:45], v[36:37], 0, s[8:9]
	v_lshl_add_u64 v[46:47], v[38:39], 0, s[8:9]
	s_mov_b64 s[8:9], 0x1800
	v_lshlrev_b64 v[2:3], 12, v[32:33]
	v_and_b32_e32 v0, 63, v0
	v_lshl_add_u64 v[48:49], v[36:37], 0, s[8:9]
	v_lshl_add_u64 v[50:51], v[38:39], 0, s[8:9]
	s_mov_b64 s[8:9], 0x1c00
	v_lshl_or_b32 v2, v0, 3, v2
	v_lshl_add_u64 v[52:53], v[36:37], 0, s[8:9]
	v_lshl_add_u64 v[54:55], v[38:39], 0, s[8:9]
	v_lshl_add_u64 v[0:1], s[4:5], 0, v[2:3]
	s_mov_b64 s[8:9], 0x23d30000
	v_lshl_add_u64 v[56:57], v[0:1], 0, s[8:9]
	s_ashr_i32 s19, s18, 31
	v_lshlrev_b64 v[0:1], 13, v[32:33]
	s_mul_i32 s44, s34, 3
	s_lshl_b64 s[28:29], s[18:19], 12
	v_lshl_add_u64 v[58:59], s[6:7], 0, v[0:1]
	s_lshl_b64 s[30:31], s[18:19], 13
	s_mov_b64 s[34:35], 0
	s_andn2_b64 vcc, exec, s[26:27]
	s_cbranch_vccnz .Lln_nohoist
	global_load_dwordx4 v[88:91], v[36:37], off
	global_load_dwordx4 v[120:123], v[38:39], off
	global_load_dwordx4 v[92:95], v[36:37], off offset:1024
	global_load_dwordx4 v[124:127], v[38:39], off offset:1024
	global_load_dwordx4 v[96:99], v[36:37], off offset:2048
	global_load_dwordx4 v[128:131], v[38:39], off offset:2048
	global_load_dwordx4 v[100:103], v[36:37], off offset:3072
	global_load_dwordx4 v[132:135], v[38:39], off offset:3072
	global_load_dwordx4 v[104:107], v[40:41], off
	global_load_dwordx4 v[136:139], v[42:43], off
	global_load_dwordx4 v[108:111], v[44:45], off
	global_load_dwordx4 v[140:143], v[46:47], off
	global_load_dwordx4 v[112:115], v[48:49], off
	global_load_dwordx4 v[144:147], v[50:51], off
	global_load_dwordx4 v[116:119], v[52:53], off
	global_load_dwordx4 v[150:153], v[54:55], off
	s_waitcnt vmcnt(0)
.Lln_nohoist:
	s_branch .LBB0_345

; __device__ __forceinline__ void row_stats(const f32x4 (&v)[8], float& mean, float& rstd) {
;     float s = 0.f;
; #pragma unroll
;     for (int i = 0; i < 8; ++i) s += v[i][0] + v[i][1] + v[i][2] + v[i][3];
;     mean = wsum(s) * (1.f / 2048.f);
;     float q = 0.f;
; #pragma unroll
;     for (int i = 0; i < 8; ++i) { const f32x4 d = v[i] - mean; q += d[0] * d[0] + d[1] * d[1] + d[2] * d[2] + d[3] * d[3]; }
;     rstd = rsqrtf(wsum(q) * (1.f / 2048.f) + LN_EPS);
; __device__ void phase_ln(const Params& p, int l) {
;     ...
;         for (int i = 0; i < 8; ++i) v[i] = *(const f32x4*)(src + i * 256 + lane * 4);
;         float mean, rstd;
;         if (l > 0) {
.LBB0_350:
	v_lshlrev_b32_e32 v148, 2, v34
	v_lshl_add_u64 v[0:1], v[0:1], 0, v[148:149]
	global_load_dwordx4 v[28:31], v[0:1], off
	global_load_dwordx4 v[24:27], v[0:1], off offset:1024
	global_load_dwordx4 v[20:23], v[0:1], off offset:2048
	global_load_dwordx4 v[16:19], v[0:1], off offset:3072
	v_add_co_u32_e32 v0, vcc, 0x1000, v0
	s_nop 1
	v_addc_co_u32_e32 v1, vcc, 0, v1, vcc
	global_load_dwordx4 v[12:15], v[0:1], off
	global_load_dwordx4 v[8:11], v[0:1], off offset:1024
	global_load_dwordx4 v[4:7], v[0:1], off offset:2048
	s_nop 0
	global_load_dwordx4 v[0:3], v[0:1], off offset:3072
	s_andn2_b64 vcc, exec, s[26:27]
	s_cbranch_vccnz .LBB0_352
	s_waitcnt vmcnt(0)
	v_add_f32_e32 v35, v28, v29
	v_add_f32_e32 v35, v30, v35
	v_add_f32_e32 v61, v24, v25
	v_add_f32_e32 v35, v31, v35
	v_add_f32_e32 v61, v26, v61
	v_add_f32_e32 v35, 0, v35
	v_add_f32_e32 v61, v27, v61
	v_add_f32_e32 v35, v35, v61
	v_add_f32_e32 v61, v20, v21
	v_add_f32_e32 v61, v22, v61
	v_add_f32_e32 v61, v23, v61
	v_add_f32_e32 v35, v35, v61
	v_add_f32_e32 v61, v16, v17
	v_mov_b32_e32 v64, v12
	v_mov_b32_e32 v65, v8
	v_mov_b32_e32 v66, v13
	v_mov_b32_e32 v67, v9
	v_add_f32_e32 v61, v18, v61
	v_pk_add_f32 v[64:65], v[64:65], v[66:67]
	v_mov_b32_e32 v66, v14
	v_mov_b32_e32 v67, v10
	v_add_f32_e32 v61, v19, v61
	v_pk_add_f32 v[64:65], v[66:67], v[64:65]
	v_mov_b32_e32 v66, v15
	v_mov_b32_e32 v67, v11
	v_add_f32_e32 v35, v35, v61
	v_pk_add_f32 v[64:65], v[66:67], v[64:65]
	v_mov_b32_e32 v66, v5
	v_add_f32_e32 v35, v35, v64
	v_add_f32_e32 v35, v35, v65
	v_mov_b32_e32 v64, v4
	v_mov_b32_e32 v65, v0
	v_mov_b32_e32 v67, v1
	v_pk_add_f32 v[64:65], v[64:65], v[66:67]
	v_mov_b32_e32 v66, v6
	v_mov_b32_e32 v67, v2
	v_pk_add_f32 v[64:65], v[66:67], v[64:65]
	v_mov_b32_e32 v66, v7
	v_mov_b32_e32 v67, v3
	v_pk_add_f32 v[64:65], v[66:67], v[64:65]
	v_cmp_lt_i32_e32 vcc, v211, v210
	v_add_f32_e32 v35, v35, v64
	v_add_f32_e32 v35, v35, v65
	v_cndmask_b32_e32 v61, v208, v211, vcc
	v_lshlrev_b32_e32 v61, 2, v61
	ds_bpermute_b32 v64, v61, v35
	v_cmp_lt_i32_e32 vcc, v212, v210
	v_lshl_add_u64 v[74:75], v[62:63], 0, v[148:149]
	s_waitcnt lgkmcnt(0)
	v_add_f32_e32 v35, v35, v64
	v_cndmask_b32_e32 v64, v208, v212, vcc
	v_lshlrev_b32_e32 v68, 2, v64
	ds_bpermute_b32 v64, v68, v35
	v_cmp_lt_i32_e32 vcc, v213, v210
	s_waitcnt lgkmcnt(0)
	v_add_f32_e32 v35, v35, v64
	v_cndmask_b32_e32 v64, v208, v213, vcc
	v_lshlrev_b32_e32 v69, 2, v64
	ds_bpermute_b32 v64, v69, v35
	v_cmp_lt_i32_e32 vcc, v214, v210
	s_waitcnt lgkmcnt(0)
	v_add_f32_e32 v35, v35, v64
	v_cndmask_b32_e32 v64, v208, v214, vcc
	v_lshlrev_b32_e32 v70, 2, v64
	ds_bpermute_b32 v64, v70, v35
	v_cmp_lt_i32_e32 vcc, v215, v210
	s_waitcnt lgkmcnt(0)
	v_add_f32_e32 v35, v35, v64
	v_cndmask_b32_e32 v64, v208, v215, vcc
	v_lshlrev_b32_e32 v71, 2, v64
	ds_bpermute_b32 v64, v71, v35
	v_cmp_lt_i32_e32 vcc, v216, v210
	s_waitcnt lgkmcnt(0)
	v_add_f32_e32 v35, v35, v64
	v_cndmask_b32_e32 v64, v208, v216, vcc
	v_lshlrev_b32_e32 v72, 2, v64
	ds_bpermute_b32 v64, v72, v35
	s_waitcnt lgkmcnt(0)
	v_add_f32_e32 v35, v35, v64
	v_fmac_f32_e32 v29, 0xba000000, v35
	v_fmac_f32_e32 v25, 0xba000000, v35
	v_fmamk_f32 v28, v35, 0xba000000, v28
	v_mul_f32_e32 v64, v29, v29
	v_fmamk_f32 v24, v35, 0xba000000, v24
	v_mul_f32_e32 v65, v25, v25
	v_fmamk_f32 v30, v35, 0xba000000, v30
	v_fmac_f32_e32 v64, v28, v28
	v_fmamk_f32 v26, v35, 0xba000000, v26
	v_fmac_f32_e32 v65, v24, v24
	v_fmamk_f32 v31, v35, 0xba000000, v31
	v_fmac_f32_e32 v64, v30, v30
	v_fmamk_f32 v27, v35, 0xba000000, v27
	v_fmac_f32_e32 v65, v26, v26
	v_fmac_f32_e32 v64, v31, v31
	v_fmac_f32_e32 v65, v27, v27
	v_fmac_f32_e32 v21, 0xba000000, v35
	v_add_f32_e32 v64, v64, v65
	v_fmamk_f32 v20, v35, 0xba000000, v20
	v_mul_f32_e32 v65, v21, v21
	v_fmamk_f32 v22, v35, 0xba000000, v22
	v_fmac_f32_e32 v65, v20, v20
	v_fmamk_f32 v23, v35, 0xba000000, v23
	v_fmac_f32_e32 v65, v22, v22
	v_fmac_f32_e32 v65, v23, v23
	v_fmac_f32_e32 v17, 0xba000000, v35
	v_add_f32_e32 v64, v65, v64
	v_fmamk_f32 v16, v35, 0xba000000, v16
	v_mul_f32_e32 v65, v17, v17
	v_fmamk_f32 v18, v35, 0xba000000, v18
	v_fmac_f32_e32 v65, v16, v16
	v_fmamk_f32 v19, v35, 0xba000000, v19
	v_fmac_f32_e32 v65, v18, v18
	v_fmamk_f32 v13, v35, 0xba000000, v13
	v_fmamk_f32 v9, v35, 0xba000000, v9
	v_fmac_f32_e32 v65, v19, v19
	v_fmac_f32_e32 v12, 0xba000000, v35
	v_fmac_f32_e32 v8, 0xba000000, v35
	v_mov_b32_e32 v66, v9
	v_mov_b32_e32 v67, v13
	v_add_f32_e32 v73, v65, v64
	v_fmamk_f32 v14, v35, 0xba000000, v14
	v_fmamk_f32 v10, v35, 0xba000000, v10
	v_mov_b32_e32 v64, v8
	v_mov_b32_e32 v65, v12
	v_pk_mul_f32 v[66:67], v[66:67], v[66:67]
	v_fmamk_f32 v15, v35, 0xba000000, v15
	v_fmamk_f32 v11, v35, 0xba000000, v11
	v_pk_fma_f32 v[64:65], v[64:65], v[64:65], v[66:67]
	v_mov_b32_e32 v66, v10
	v_mov_b32_e32 v67, v14
	v_pk_fma_f32 v[64:65], v[66:67], v[66:67], v[64:65]
	v_mov_b32_e32 v66, v11
	v_mov_b32_e32 v67, v15
	v_pk_fma_f32 v[64:65], v[66:67], v[66:67], v[64:65]
	v_fmamk_f32 v5, v35, 0xba000000, v5
	v_fmamk_f32 v1, v35, 0xba000000, v1
	v_add_f32_e32 v65, v65, v73
	v_fmac_f32_e32 v4, 0xba000000, v35
	v_fmac_f32_e32 v0, 0xba000000, v35
	v_mov_b32_e32 v66, v1
	v_mov_b32_e32 v67, v5
	v_add_f32_e32 v73, v64, v65
	v_fmamk_f32 v6, v35, 0xba000000, v6
	v_mov_b32_e32 v64, v0
	v_mov_b32_e32 v65, v4
	v_pk_mul_f32 v[66:67], v[66:67], v[66:67]
	v_fmamk_f32 v2, v35, 0xba000000, v2
	v_pk_fma_f32 v[64:65], v[64:65], v[64:65], v[66:67]
	v_mov_b32_e32 v66, v2
	v_mov_b32_e32 v67, v6
	v_fmamk_f32 v7, v35, 0xba000000, v7
	v_fmamk_f32 v3, v35, 0xba000000, v3
	v_pk_fma_f32 v[64:65], v[66:67], v[66:67], v[64:65]
	v_mov_b32_e32 v66, v3
	v_mov_b32_e32 v67, v7
	v_pk_fma_f32 v[64:65], v[66:67], v[66:67], v[64:65]
	s_nop 0
	v_add_f32_e32 v35, v65, v73
	v_add_f32_e32 v35, v64, v35
	ds_bpermute_b32 v61, v61, v35
	s_waitcnt lgkmcnt(0)
; #define TIDX tid_()
; #define BIDX bid_()
; #define GDIM gdim_()
; __device__ __forceinline__ void row_stats(const f32x4 (&v)[8], float& mean, float& rstd) {
;     ...
;     mean = wsum(s) * (1.f / 2048.f);
;     float q = 0.f;
; #pragma unroll
;     for (int i = 0; i < 8; ++i) { const f32x4 d = v[i] - mean; q += d[0] * d[0] + d[1] * d[1] + d[2] * d[2] + d[3] * d[3]; }
;     rstd = rsqrtf(wsum(q) * (1.f / 2048.f) + LN_EPS);
; }
; __device__ void phase_ln(const Params& p, int l) {
;     const int wid = TIDX >> 6, lane = TIDX & 63;
;     const int nw = GDIM * 8;
;     const bool fin = (l == DEPTH);
;     for (int row = BIDX * 8 + wid; row < MROWS; row += nw) {
;         const bool isctx = row < CTXROWS;
;         if (fin && isctx) continue;
;         const int b = isctx ? (row >> 8) : ((row - CTXROWS) >> 13);
;         float* rw = isctx ? p.RC + (size_t)row * D : p.out + (size_t)(row - CTXROWS) * D;
;         const float* src = (l == 0) ? (isctx ? p.ctx + (size_t)row * D : p.x + (size_t)(row - CTXROWS) * D) : rw;
;         f32x4 v[8];
; #pragma unroll
;         for (int i = 0; i < 8; ++i) v[i] = *(const f32x4*)(src + i * 256 + lane * 4);
;         float mean, rstd;
;         if (l > 0) {
;             row_stats(v, mean, rstd);
;             const float* g = p.ln_g + (size_t)(l - 1) * D; const float* bb = p.ln_b + (size_t)(l - 1) * D;
; #pragma unroll
;             for (int i = 0; i < 8; ++i) { const f32x4 gv = *(const f32x4*)(g + i * 256 + lane * 4), bv = *(const f32x4*)(bb + i * 256 + lane * 4);
;                 v[i] = (v[i] - mean) * rstd * gv + bv; *(f32x4*)(rw + i * 256 + lane * 4) = v[i]; }
	v_add_f32_e32 v35, v35, v61
	ds_bpermute_b32 v61, v68, v35
	s_waitcnt lgkmcnt(0)
	v_add_f32_e32 v35, v35, v61
	ds_bpermute_b32 v61, v69, v35
	s_waitcnt lgkmcnt(0)
	v_add_f32_e32 v35, v35, v61
	ds_bpermute_b32 v61, v70, v35
	s_waitcnt lgkmcnt(0)
	v_add_f32_e32 v35, v35, v61
	ds_bpermute_b32 v61, v71, v35
	v_mov_b64_e32 v[64:65], v[88:89]
	v_mov_b64_e32 v[66:67], v[90:91]
	v_mov_b64_e32 v[68:69], v[120:121]
	v_mov_b64_e32 v[70:71], v[122:123]
	s_waitcnt lgkmcnt(0)
	v_add_f32_e32 v35, v35, v61
	ds_bpermute_b32 v61, v72, v35
	s_waitcnt lgkmcnt(0)
	v_add_f32_e32 v35, v35, v61
	v_fmamk_f32 v35, v35, 0x3a000000, v207
	v_mul_f32_e32 v61, 0x4b800000, v35
	v_cmp_gt_f32_e32 vcc, s41, v35
	s_nop 1
	v_cndmask_b32_e32 v35, v35, v61, vcc
	v_rsq_f32_e32 v35, v35
	s_nop 0
	v_mul_f32_e32 v61, 0x45800000, v35
	v_cndmask_b32_e32 v72, v35, v61, vcc
	v_pk_mul_f32 v[28:29], v[28:29], v[72:73] op_sel_hi:[1,0]
	v_pk_mul_f32 v[30:31], v[30:31], v[72:73] op_sel_hi:[1,0]
	v_pk_mul_f32 v[26:27], v[26:27], v[72:73] op_sel_hi:[1,0]
	v_pk_mul_f32 v[24:25], v[24:25], v[72:73] op_sel_hi:[1,0]
	v_pk_mul_f32 v[22:23], v[22:23], v[72:73] op_sel_hi:[1,0]
	v_pk_mul_f32 v[20:21], v[20:21], v[72:73] op_sel_hi:[1,0]
	v_pk_mul_f32 v[18:19], v[18:19], v[72:73] op_sel_hi:[1,0]
	v_pk_mul_f32 v[16:17], v[16:17], v[72:73] op_sel_hi:[1,0]
	v_pk_mul_f32 v[14:15], v[14:15], v[72:73] op_sel_hi:[1,0]
	v_pk_mul_f32 v[12:13], v[12:13], v[72:73] op_sel_hi:[1,0]
	v_pk_mul_f32 v[10:11], v[10:11], v[72:73] op_sel_hi:[1,0]
	v_pk_mul_f32 v[8:9], v[8:9], v[72:73] op_sel_hi:[1,0]
	v_pk_mul_f32 v[6:7], v[6:7], v[72:73] op_sel_hi:[1,0]
	v_pk_mul_f32 v[4:5], v[4:5], v[72:73] op_sel_hi:[1,0]
	v_pk_mul_f32 v[2:3], v[2:3], v[72:73] op_sel_hi:[1,0]
	v_pk_mul_f32 v[0:1], v[0:1], v[72:73] op_sel_hi:[1,0]
	v_pk_fma_f32 v[30:31], v[66:67], v[30:31], v[70:71]
	v_pk_fma_f32 v[28:29], v[64:65], v[28:29], v[68:69]
	global_store_dwordx4 v[74:75], v[28:31], off
	v_mov_b64_e32 v[62:63], v[92:93]
	v_mov_b64_e32 v[64:65], v[94:95]
	v_mov_b64_e32 v[66:67], v[124:125]
	v_mov_b64_e32 v[68:69], v[126:127]
	v_add_co_u32_e32 v70, vcc, s69, v74
	v_pk_fma_f32 v[24:25], v[62:63], v[24:25], v[66:67]
	v_pk_fma_f32 v[26:27], v[64:65], v[26:27], v[68:69]
	global_store_dwordx4 v[74:75], v[24:27], off offset:1024
	v_mov_b64_e32 v[62:63], v[96:97]
	v_mov_b64_e32 v[64:65], v[98:99]
	v_mov_b64_e32 v[66:67], v[128:129]
	v_mov_b64_e32 v[68:69], v[130:131]
	v_addc_co_u32_e32 v71, vcc, 0, v75, vcc
	v_pk_fma_f32 v[20:21], v[62:63], v[20:21], v[66:67]
	v_pk_fma_f32 v[22:23], v[64:65], v[22:23], v[68:69]
	global_store_dwordx4 v[74:75], v[20:23], off offset:2048
	v_mov_b64_e32 v[62:63], v[100:101]
	v_mov_b64_e32 v[64:65], v[102:103]
	v_mov_b64_e32 v[66:67], v[132:133]
	v_mov_b64_e32 v[68:69], v[134:135]
	v_pk_fma_f32 v[16:17], v[62:63], v[16:17], v[66:67]
	v_pk_fma_f32 v[18:19], v[64:65], v[18:19], v[68:69]
	global_store_dwordx4 v[74:75], v[16:19], off offset:3072
	v_mov_b64_e32 v[62:63], v[104:105]
	v_mov_b64_e32 v[64:65], v[106:107]
	v_mov_b64_e32 v[66:67], v[136:137]
	v_mov_b64_e32 v[68:69], v[138:139]
	v_pk_fma_f32 v[12:13], v[62:63], v[12:13], v[66:67]
	v_pk_fma_f32 v[14:15], v[64:65], v[14:15], v[68:69]
	global_store_dwordx4 v[70:71], v[12:15], off
	v_mov_b64_e32 v[62:63], v[108:109]
	v_mov_b64_e32 v[64:65], v[110:111]
	v_mov_b64_e32 v[66:67], v[140:141]
	v_mov_b64_e32 v[68:69], v[142:143]
	v_pk_fma_f32 v[8:9], v[62:63], v[8:9], v[66:67]
	v_pk_fma_f32 v[10:11], v[64:65], v[10:11], v[68:69]
	global_store_dwordx4 v[70:71], v[8:11], off offset:1024
	v_mov_b64_e32 v[62:63], v[112:113]
	v_mov_b64_e32 v[64:65], v[114:115]
	v_mov_b64_e32 v[66:67], v[144:145]
	v_mov_b64_e32 v[68:69], v[146:147]
	v_pk_fma_f32 v[4:5], v[62:63], v[4:5], v[66:67]
	v_pk_fma_f32 v[6:7], v[64:65], v[6:7], v[68:69]
	global_store_dwordx4 v[70:71], v[4:7], off offset:2048
	v_mov_b64_e32 v[62:63], v[116:117]
	v_mov_b64_e32 v[64:65], v[118:119]
	v_mov_b64_e32 v[66:67], v[150:151]
	v_mov_b64_e32 v[68:69], v[152:153]
	v_pk_fma_f32 v[0:1], v[62:63], v[0:1], v[66:67]
	v_pk_fma_f32 v[2:3], v[64:65], v[2:3], v[68:69]
	global_store_dwordx4 v[70:71], v[0:3], off offset:3072
